# v9 plus no transcendental VALU at the head of a half-iteration: the four post-barrier exp2 ops issued in the previous half's PV MFMA gaps
# speedup vs baseline: 1.0020x; 1.0020x over previous
; #define DMA(slot, t) do { \
;     __builtin_amdgcn_global_load_lds((const unsigned*)(Kg + (long)(t) * (64 * 256)), (LAS unsigned*)(L3 + K_OFF + (slot) * SHM_T + wid * 1024), 16, 0, 0); \
;     __builtin_amdgcn_global_load_lds((const unsigned*)(Vg + (long)(t) * 8192), (LAS unsigned*)(L3 + (slot) * SHM_T + wid * 1024), 16, 0, 0); } while (0)
; #define BAR() do { asm volatile("s_waitcnt lgkmcnt(0)" ::: "memory"); __builtin_amdgcn_s_barrier(); asm volatile("" ::: "memory"); } while (0)
; #define WAITV(n) asm volatile("s_waitcnt vmcnt(" #n ")" ::: "memory")
; #define QKT(P0, P1, b) qkt(P0, P1, nm, K_lds + (b) * SHM_T, qr, ko, c00, c01, c10, c11)
; __device__ __forceinline__ void partialSM_first(f32x16& p0, f32x16& p1, f32x16& nm) {
;   const float delta = max32(p0, p1) - PSHIFT;
;   for (int r = 0; r < 16; ++r) { p0[r] -= delta; p1[r] -= delta; nm[r] -= delta; }
;   for (int r = 0; r < 16; ++r) p0[r] = __builtin_amdgcn_exp2f(p0[r]);
; }
; __device__ __forceinline__ void finishSM(f32x16& p0, f32x16& p1, v8i& pf) {
;   for (int r = 0; r < 16; ++r) p1[r] = __builtin_amdgcn_exp2f(p1[r]);
; __device__ __forceinline__ void body(const unsigned char* Q8b, const unsigned char* K8h, const unsigned char* VT8h, const bf16_t* Gb, bf16_t* Ob, int seq, char* lds, const int wid, ...
;     ...
;   if (!pre) { DMA(0, 0); DMA(1, 1); } else BAR();
;   DMA(2, 2);
;   WAITV(2); BAR();
;   QKT(pA0, pA1, 0); partialSM_first(pA0, pA1, nm);
.LBB0_371:
	s_mov_b32 m0, s76
	v_lshl_add_u64 v[2:3], v[220:221], 0, s[42:43]
	global_load_lds_dwordx4 v[2:3], off
	v_lshl_add_u64 v[2:3], v[222:223], 0, s[38:39]
	s_mov_b32 m0, s78
	s_nop 0
	global_load_lds_dwordx4 v[2:3], off
	s_waitcnt vmcnt(2)
	s_waitcnt lgkmcnt(0)
	s_barrier
	ds_read_b128 v[22:25], v243 offset:32768
	ds_read_b128 v[18:21], v242 offset:32768
	ds_read_b128 v[34:37], v242 offset:36864
	ds_read_b128 v[38:41], v243 offset:36864
	v_mov_b64_e32 v[2:3], s[8:9]
	v_mov_b64_e32 v[4:5], s[10:11]
	v_mov_b64_e32 v[6:7], s[12:13]
	v_mov_b64_e32 v[8:9], s[14:15]
	v_mov_b64_e32 v[10:11], s[16:17]
	v_mov_b64_e32 v[12:13], s[18:19]
	v_mov_b64_e32 v[14:15], s[20:21]
	v_mov_b64_e32 v[16:17], s[22:23]
	s_nop 1
	s_waitcnt vmcnt(0) lgkmcnt(0)
	v_mfma_scale_f32_32x32x64_f8f6f4 v[18:33], v[18:25], v[176:183], v[2:17], v240, v239 op_sel_hi:[0,0,0]
	s_xor_b64 s[48:49], s[54:55], -1
	s_add_u32 s56, s56, s36
	s_addc_u32 s57, s57, 0
	v_lshl_add_u64 v[224:225], v[216:217], 0, s[58:59]
	v_lshl_add_u64 v[226:227], v[218:219], 0, s[56:57]
	s_mov_b32 s45, 0
	s_mov_b32 s47, 0
	v_mfma_scale_f32_32x32x64_f8f6f4 v[2:17], v[34:41], v[176:183], v[2:17], v240, v239 op_sel_hi:[0,0,0]
	ds_read_b128 v[38:41], v245 offset:32768
	ds_read_b128 v[34:37], v244 offset:32768
	ds_read_b128 v[42:45], v244 offset:36864
	ds_read_b128 v[46:49], v245 offset:36864
	s_waitcnt lgkmcnt(2)
	v_mfma_scale_f32_32x32x64_f8f6f4 v[18:33], v[34:41], v[184:191], v[18:33], v240, v239 op_sel_hi:[0,0,0]
	s_waitcnt lgkmcnt(0)
	v_mfma_scale_f32_32x32x64_f8f6f4 v[2:17], v[42:49], v[184:191], v[2:17], v240, v239 op_sel_hi:[0,0,0]
	s_nop 15
	s_nop 1
	v_max_f32_e32 v1, v19, v19
	v_max_f32_e32 v34, v18, v18
	v_max_f32_e32 v1, v34, v1
	v_max3_f32 v1, v1, v20, v21
	v_max3_f32 v1, v1, v22, v23
	v_max3_f32 v1, v1, v24, v25
	v_max3_f32 v1, v1, v26, v27
	v_max3_f32 v1, v1, v28, v29
	v_max3_f32 v1, v1, v30, v31
	v_max3_f32 v1, v1, v32, v33
	v_max3_f32 v1, v1, v2, v3
	v_max3_f32 v1, v1, v4, v5
	v_max3_f32 v1, v1, v6, v7
	v_max3_f32 v1, v1, v8, v9
	v_max3_f32 v1, v1, v10, v11
	v_max3_f32 v1, v1, v12, v13
	v_max3_f32 v1, v1, v14, v15
	v_max3_f32 v1, v1, v16, v17
	v_mov_b32_e32 v34, v1
	s_nop 1
	v_permlane32_swap_b32_e32 v1, v34
	v_max_f32_e32 v34, v34, v34
	v_max_f32_e32 v1, v1, v1
	v_max_f32_e32 v1, v1, v34
	v_add_f32_e32 v1, 0xc0a00000, v1
	v_sub_f32_e32 v18, v18, v1
	v_sub_f32_e32 v19, v19, v1
	v_sub_f32_e32 v20, v20, v1
	v_sub_f32_e32 v21, v21, v1
	v_sub_f32_e32 v22, v22, v1
	v_sub_f32_e32 v23, v23, v1
	v_sub_f32_e32 v24, v24, v1
	v_sub_f32_e32 v25, v25, v1
	v_sub_f32_e32 v26, v26, v1
	v_sub_f32_e32 v27, v27, v1
	v_sub_f32_e32 v28, v28, v1
	v_sub_f32_e32 v29, v29, v1
	v_sub_f32_e32 v30, v30, v1
	v_sub_f32_e32 v31, v31, v1
	v_sub_f32_e32 v32, v32, v1
	v_sub_f32_e32 v33, v33, v1
	v_exp_f32_e32 v144, v18
	v_exp_f32_e32 v145, v19
	v_exp_f32_e32 v146, v20
	v_exp_f32_e32 v147, v21
	v_exp_f32_e32 v148, v22
	v_exp_f32_e32 v149, v23
	v_exp_f32_e32 v150, v24
	v_exp_f32_e32 v151, v25
	v_exp_f32_e32 v152, v26
	v_exp_f32_e32 v153, v27
	v_exp_f32_e32 v154, v28
	v_exp_f32_e32 v155, v29
	v_exp_f32_e32 v156, v30
	v_exp_f32_e32 v157, v31
	v_exp_f32_e32 v158, v32
	v_exp_f32_e32 v159, v33
	v_sub_f32_e32 v125, v15, v1
	v_sub_f32_e32 v124, v14, v1
	v_mov_b32_e32 v14, v0
	v_mov_b32_e32 v15, v0
	v_sub_f32_e32 v96, 0x40a00000, v1
	v_sub_f32_e32 v127, v17, v1
	v_sub_f32_e32 v126, v16, v1
	v_sub_f32_e32 v123, v13, v1
	v_sub_f32_e32 v122, v12, v1
	v_sub_f32_e32 v121, v11, v1
	v_sub_f32_e32 v120, v10, v1
	v_sub_f32_e32 v119, v9, v1
	v_sub_f32_e32 v118, v8, v1
	v_sub_f32_e32 v117, v7, v1
	v_sub_f32_e32 v116, v6, v1
	v_sub_f32_e32 v115, v5, v1
	v_sub_f32_e32 v114, v4, v1
	v_sub_f32_e32 v113, v3, v1
	v_sub_f32_e32 v112, v2, v1
	v_mov_b32_e32 v1, v0
	v_mov_b32_e32 v2, v0
	v_mov_b32_e32 v3, v0
	v_mov_b32_e32 v4, v0
	v_mov_b32_e32 v5, v0
	v_mov_b32_e32 v6, v0
	v_mov_b32_e32 v7, v0
	v_mov_b32_e32 v8, v0
	v_mov_b32_e32 v9, v0
	v_mov_b32_e32 v10, v0
	v_mov_b32_e32 v11, v0
	v_mov_b32_e32 v12, v0
	v_mov_b32_e32 v13, v0
	v_mov_b64_e32 v[78:79], v[14:15]
	v_mov_b64_e32 v[62:63], v[14:15]
	v_mov_b64_e32 v[46:47], v[14:15]
	v_mov_b64_e32 v[30:31], v[14:15]
	v_mov_b64_e32 v[94:95], v[14:15]
	v_mov_b32_e32 v97, v96
	v_mov_b32_e32 v98, v96
	v_mov_b32_e32 v99, v96
	v_mov_b32_e32 v100, v96
	v_mov_b32_e32 v101, v96
	v_mov_b32_e32 v102, v96
	v_mov_b32_e32 v103, v96
	v_mov_b32_e32 v104, v96
	v_mov_b32_e32 v105, v96
	v_mov_b32_e32 v106, v96
	v_mov_b32_e32 v107, v96
	v_mov_b32_e32 v108, v96
	v_mov_b32_e32 v109, v96
	v_mov_b32_e32 v110, v96
	v_mov_b32_e32 v111, v96
	v_mov_b64_e32 v[76:77], v[12:13]
	v_mov_b64_e32 v[74:75], v[10:11]
	v_mov_b64_e32 v[72:73], v[8:9]
	v_mov_b64_e32 v[70:71], v[6:7]
	v_mov_b64_e32 v[68:69], v[4:5]
	v_mov_b64_e32 v[66:67], v[2:3]
	v_mov_b64_e32 v[64:65], v[0:1]
	v_mov_b64_e32 v[60:61], v[12:13]
	v_mov_b64_e32 v[58:59], v[10:11]
	v_mov_b64_e32 v[56:57], v[8:9]
	v_mov_b64_e32 v[54:55], v[6:7]
	v_mov_b64_e32 v[52:53], v[4:5]
	v_mov_b64_e32 v[50:51], v[2:3]
	v_mov_b64_e32 v[48:49], v[0:1]
	v_mov_b64_e32 v[44:45], v[12:13]
	v_mov_b64_e32 v[42:43], v[10:11]
	v_mov_b64_e32 v[40:41], v[8:9]
	v_mov_b64_e32 v[38:39], v[6:7]
	v_mov_b64_e32 v[36:37], v[4:5]
	v_mov_b64_e32 v[34:35], v[2:3]
	v_mov_b64_e32 v[32:33], v[0:1]
	v_mov_b64_e32 v[28:29], v[12:13]
	v_mov_b64_e32 v[26:27], v[10:11]
	v_mov_b64_e32 v[24:25], v[8:9]
	v_mov_b64_e32 v[22:23], v[6:7]
	v_mov_b64_e32 v[20:21], v[4:5]
	v_mov_b64_e32 v[18:19], v[2:3]
	v_mov_b64_e32 v[16:17], v[0:1]
	v_mov_b64_e32 v[92:93], v[12:13]
	v_mov_b64_e32 v[90:91], v[10:11]
	v_mov_b64_e32 v[88:89], v[8:9]
	v_mov_b64_e32 v[86:87], v[6:7]
	v_mov_b64_e32 v[84:85], v[4:5]
	v_mov_b64_e32 v[82:83], v[2:3]
	v_mov_b64_e32 v[80:81], v[0:1]
	v_exp_f32_e32 v13, v112
	v_exp_f32_e32 v10, v113
	v_exp_f32_e32 v11, v114
	v_exp_f32_e32 v12, v115
	s_branch .LBB0_374
; __device__ __forceinline__ void finishSM(f32x16& p0, f32x16& p1, v8i& pf) {
;   for (int r = 0; r < 16; ++r) p1[r] = __builtin_amdgcn_exp2f(p1[r]);
.LBB0_372:
	s_or_b64 exec, exec, s[56:57]
	s_waitcnt lgkmcnt(0)
	v_add_u32_e32 v1, s67, v237
	ds_read_b128 v[2:5], v1 offset:224
	ds_read_b128 v[6:9], v1 offset:192
	ds_read_b128 v[10:13], v1 offset:160
	ds_read_b128 v[128:131], v1 offset:128
	s_waitcnt lgkmcnt(0)
	v_pk_mul_f32 v[76:77], v[76:77], v[2:3]
	v_pk_mul_f32 v[72:73], v[72:73], v[6:7]
	v_pk_mul_f32 v[68:69], v[68:69], v[10:11]
	v_pk_mul_f32 v[78:79], v[78:79], v[4:5]
	v_pk_mul_f32 v[74:75], v[74:75], v[8:9]
	v_pk_mul_f32 v[70:71], v[70:71], v[12:13]
	v_pk_mul_f32 v[66:67], v[66:67], v[130:131]
	v_pk_mul_f32 v[64:65], v[64:65], v[128:129]
	v_pk_mul_f32 v[60:61], v[60:61], v[2:3]
	v_pk_mul_f32 v[56:57], v[56:57], v[6:7]
	v_pk_mul_f32 v[52:53], v[52:53], v[10:11]
	v_pk_mul_f32 v[62:63], v[62:63], v[4:5]
	v_pk_mul_f32 v[58:59], v[58:59], v[8:9]
	v_pk_mul_f32 v[54:55], v[54:55], v[12:13]
	v_pk_mul_f32 v[50:51], v[50:51], v[130:131]
	v_pk_mul_f32 v[48:49], v[48:49], v[128:129]
	v_pk_mul_f32 v[44:45], v[44:45], v[2:3]
	v_pk_mul_f32 v[40:41], v[40:41], v[6:7]
	v_pk_mul_f32 v[36:37], v[36:37], v[10:11]
	v_pk_mul_f32 v[46:47], v[46:47], v[4:5]
	v_pk_mul_f32 v[42:43], v[42:43], v[8:9]
	v_pk_mul_f32 v[38:39], v[38:39], v[12:13]
	v_pk_mul_f32 v[34:35], v[34:35], v[130:131]
	v_pk_mul_f32 v[32:33], v[32:33], v[128:129]
	v_pk_mul_f32 v[28:29], v[28:29], v[2:3]
	v_pk_mul_f32 v[24:25], v[24:25], v[6:7]
	v_pk_mul_f32 v[20:21], v[20:21], v[10:11]
	v_pk_mul_f32 v[30:31], v[30:31], v[4:5]
	v_pk_mul_f32 v[26:27], v[26:27], v[8:9]
	v_pk_mul_f32 v[22:23], v[22:23], v[12:13]
	v_pk_mul_f32 v[18:19], v[18:19], v[130:131]
	v_pk_mul_f32 v[16:17], v[16:17], v[128:129]
	v_pk_mul_f32 v[92:93], v[92:93], v[2:3]
	v_pk_mul_f32 v[88:89], v[88:89], v[6:7]
	v_pk_mul_f32 v[84:85], v[84:85], v[10:11]
	v_pk_mul_f32 v[94:95], v[94:95], v[4:5]
	v_pk_mul_f32 v[90:91], v[90:91], v[8:9]
	v_pk_mul_f32 v[86:87], v[86:87], v[12:13]
	v_pk_mul_f32 v[82:83], v[82:83], v[130:131]
	v_pk_mul_f32 v[80:81], v[80:81], v[128:129]
	v_exp_f32_e32 v13, v112
	v_exp_f32_e32 v10, v113
	v_exp_f32_e32 v11, v114
	v_exp_f32_e32 v12, v115

; #define SBAR() __builtin_amdgcn_sched_barrier(0)
; #define QKT(P0, P1, b) qkt(P0, P1, nm, K_lds + (b) * SHM_T, qr, ko, c00, c01, c10, c11)
; #define PIPE1() do { SGB(0x100, 8); SGB(0x400, 4); SGB(0x008, 1); SGB(0x400, 4); SGB(0x008, 1); SGB(0x400, 4); SGB(0x008, 1); SGB(0x400, 4); SGB(0x008, 1); } while (0)
; __device__ __forceinline__ void finishSM(f32x16& p0, f32x16& p1, v8i& pf) {
;   for (int r = 0; r < 16; ++r) p1[r] = __builtin_amdgcn_exp2f(p1[r]);
; #pragma unroll
;   for (int j = 0; j < 4; ++j) {
;     int a = __builtin_amdgcn_cvt_pk_fp8_f32(p0[4 * j], p0[4 * j + 1], 0, false); a = __builtin_amdgcn_cvt_pk_fp8_f32(p0[4 * j + 2], p0[4 * j + 3], a, true);
;     int b = __builtin_amdgcn_cvt_pk_fp8_f32(p1[4 * j], p1[4 * j + 1], 0, false); b = __builtin_amdgcn_cvt_pk_fp8_f32(p1[4 * j + 2], p1[4 * j + 3], b, true);
;     auto rr = __builtin_amdgcn_permlane32_swap((unsigned)a, (unsigned)b, false, false);
;     pf[2 * j] = (int)rr[0]; pf[2 * j + 1] = (int)rr[1]; }
; }
; __device__ __forceinline__ void body(const unsigned char* Q8b, const unsigned char* K8h, const unsigned char* VT8h, const bf16_t* Gb, bf16_t* Ob, int seq, char* lds, const int wid, ...
;     ...
;     SBAR(); QKT(pB0, pB1, (s0 + 1) & 3);
;     finishSM(pA0, pA1, pf); PIPE1(); SBAR();
.LBB0_374:
	ds_read_b128 v[2:5], v242 offset:40960
	ds_read_b128 v[6:9], v243 offset:40960
	ds_read_b128 v[128:131], v242 offset:45056
	ds_read_b128 v[132:135], v243 offset:45056
	ds_read_b128 v[194:197], v244 offset:40960
	ds_read_b128 v[198:201], v245 offset:40960
	ds_read_b128 v[246:249], v244 offset:45056
	ds_read_b128 v[250:253], v245 offset:45056
	s_waitcnt lgkmcnt(6)
	s_setprio 1
	v_mfma_scale_f32_32x32x64_f8f6f4 v[160:175], v[2:9], v[176:183], v[96:111], v240, v239 op_sel_hi:[0,0,0]
	v_exp_f32_e32 v6, v116
	v_exp_f32_e32 v7, v117
	v_exp_f32_e32 v8, v118
	v_exp_f32_e32 v9, v119
	v_cvt_pk_fp8_f32 v5, v6, v7
	v_cvt_pk_fp8_f32 v3, v13, v10
	v_cvt_pk_fp8_f32 v5, v8, v9 op_sel:[0,0,1]
	s_waitcnt lgkmcnt(4)
	v_mfma_scale_f32_32x32x64_f8f6f4 v[128:143], v[128:135], v[176:183], v[96:111], v240, v239 op_sel_hi:[0,0,0]
	v_exp_f32_e32 v13, v120
	v_exp_f32_e32 v14, v121
	v_exp_f32_e32 v15, v122
	v_exp_f32_e32 v112, v123
	v_cvt_pk_fp8_f32 v2, v144, v145
	v_cvt_pk_fp8_f32 v4, v148, v149
	v_cvt_pk_fp8_f32 v6, v152, v153
	v_cvt_pk_fp8_f32 v7, v13, v14
	v_cvt_pk_fp8_f32 v8, v156, v157
	v_cvt_pk_fp8_f32 v2, v146, v147 op_sel:[0,0,1]
	v_cvt_pk_fp8_f32 v3, v11, v12 op_sel:[0,0,1]
	v_cvt_pk_fp8_f32 v4, v150, v151 op_sel:[0,0,1]
	v_cvt_pk_fp8_f32 v6, v154, v155 op_sel:[0,0,1]
	v_cvt_pk_fp8_f32 v7, v15, v112 op_sel:[0,0,1]
	v_cvt_pk_fp8_f32 v8, v158, v159 op_sel:[0,0,1]
	s_waitcnt lgkmcnt(2)
	v_mfma_scale_f32_32x32x64_f8f6f4 v[160:175], v[194:201], v[184:191], v[160:175], v240, v239 op_sel_hi:[0,0,0]
	v_exp_f32_e32 v113, v124
	v_exp_f32_e32 v114, v125
	v_exp_f32_e32 v1, v126
	v_exp_f32_e32 v10, v127
	v_permlane32_swap_b32_e32 v2, v3
	v_cvt_pk_fp8_f32 v9, v113, v114
	v_permlane32_swap_b32_e32 v4, v5
	v_permlane32_swap_b32_e32 v6, v7
	v_cvt_pk_fp8_f32 v9, v1, v10 op_sel:[0,0,1]
	s_nop 1
	v_permlane32_swap_b32_e32 v8, v9
	s_waitcnt lgkmcnt(0)
	v_mfma_scale_f32_32x32x64_f8f6f4 v[128:143], v[246:253], v[184:191], v[128:143], v240, v239 op_sel_hi:[0,0,0]
	s_setprio 0
	s_add_i32 m0, s68, 0xe000
	s_nop 0
	global_load_lds_dwordx4 v192, s[98:99]
	s_add_i32 m0, s68, 0x6000
	s_nop 0
	global_load_lds_dwordx4 v193, s[100:101]
	ds_read_b128 v[194:197], v254
	ds_read_b128 v[148:151], v254 offset:2048
	ds_read_b128 v[198:201], v255
	ds_read_b128 v[152:155], v255 offset:2048
	ds_read_b128 v[120:123], v254 offset:4096
	ds_read_b128 v[112:115], v254 offset:6144
	ds_read_b128 v[124:127], v255 offset:4096
	ds_read_b128 v[116:119], v255 offset:6144
	v_max_f32_e32 v1, v160, v161
	v_max3_f32 v1, v1, v162, v163
	v_max3_f32 v1, v1, v164, v165
	v_max3_f32 v1, v1, v166, v167
	v_max3_f32 v1, v1, v168, v169
	v_max3_f32 v1, v1, v170, v171
	v_max3_f32 v1, v1, v172, v173
	v_max3_f32 v1, v1, v174, v175
	v_max3_f32 v1, v1, v128, v129
	v_max3_f32 v1, v1, v130, v131
	v_max3_f32 v1, v1, v132, v133
	v_max3_f32 v1, v1, v134, v135
	v_max3_f32 v1, v1, v136, v137
	v_max3_f32 v1, v1, v138, v139
	v_max3_f32 v1, v1, v140, v141
	v_max3_f32 v1, v1, v142, v143
	v_cmp_lt_f32_e32 vcc, s80, v1
	s_cbranch_vccnz .LBB0_383

.Lstg_b1:
	s_waitcnt lgkmcnt(5)
	v_mfma_scale_f32_32x32x64_f8f6f4 v[64:79], v[2:9], v[194:201], v[64:79], v240, v240 op_sel_hi:[0,0,0]
	v_exp_f32_e32 v144, v160
	v_exp_f32_e32 v145, v161
	v_exp_f32_e32 v146, v162
	v_exp_f32_e32 v13, v128
	s_waitcnt lgkmcnt(4)
	v_mfma_scale_f32_32x32x64_f8f6f4 v[48:63], v[2:9], v[148:155], v[48:63], v240, v240 op_sel_hi:[0,0,0]
	v_exp_f32_e32 v147, v163
	v_exp_f32_e32 v148, v164
	v_exp_f32_e32 v149, v165
	v_exp_f32_e32 v10, v129
	s_waitcnt lgkmcnt(1)
	v_mfma_scale_f32_32x32x64_f8f6f4 v[32:47], v[2:9], v[120:127], v[32:47], v240, v240 op_sel_hi:[0,0,0]
	v_exp_f32_e32 v150, v166
	v_exp_f32_e32 v151, v167
	v_exp_f32_e32 v152, v168
	v_exp_f32_e32 v11, v130
	s_waitcnt lgkmcnt(0)
	v_mfma_scale_f32_32x32x64_f8f6f4 v[16:31], v[2:9], v[112:119], v[16:31], v240, v240 op_sel_hi:[0,0,0]
	v_exp_f32_e32 v153, v169
	v_exp_f32_e32 v154, v170
	v_exp_f32_e32 v155, v171
	v_exp_f32_e32 v12, v131
	v_mfma_scale_f32_32x32x64_f8f6f4 v[80:95], v[2:9], v[228:235], v[80:95], v240, v240 op_sel_hi:[0,0,0]
	v_exp_f32_e32 v156, v172
	v_exp_f32_e32 v157, v173
	v_exp_f32_e32 v158, v174
	v_exp_f32_e32 v159, v175
	s_waitcnt vmcnt(2)
	s_cmp_eq_u32 s93, 0
	s_cbranch_scc1 .LBB0_379
	s_mov_b32 s93, 0
	s_and_saveexec_b64 s[56:57], s[4:5]
	ds_write_b32 v236, v1 offset:128
	s_or_b64 exec, exec, s[56:57]
	s_waitcnt lgkmcnt(0)
	v_add_u32_e32 v1, s67, v237
	ds_read_b128 v[2:5], v1 offset:224
	ds_read_b128 v[6:9], v1 offset:192
	ds_read_b128 v[10:13], v1 offset:160
	ds_read_b128 v[112:115], v1 offset:128
	s_waitcnt lgkmcnt(0)
	v_pk_mul_f32 v[76:77], v[76:77], v[2:3]
	v_pk_mul_f32 v[72:73], v[72:73], v[6:7]
	v_pk_mul_f32 v[68:69], v[68:69], v[10:11]
	v_pk_mul_f32 v[78:79], v[78:79], v[4:5]
	v_pk_mul_f32 v[74:75], v[74:75], v[8:9]
	v_pk_mul_f32 v[70:71], v[70:71], v[12:13]
	v_pk_mul_f32 v[66:67], v[66:67], v[114:115]
	v_pk_mul_f32 v[64:65], v[64:65], v[112:113]
	v_pk_mul_f32 v[60:61], v[60:61], v[2:3]
	v_pk_mul_f32 v[56:57], v[56:57], v[6:7]
	v_pk_mul_f32 v[52:53], v[52:53], v[10:11]
	v_pk_mul_f32 v[62:63], v[62:63], v[4:5]
	v_pk_mul_f32 v[58:59], v[58:59], v[8:9]
	v_pk_mul_f32 v[54:55], v[54:55], v[12:13]
	v_pk_mul_f32 v[50:51], v[50:51], v[114:115]
	v_pk_mul_f32 v[48:49], v[48:49], v[112:113]
	v_pk_mul_f32 v[44:45], v[44:45], v[2:3]
	v_pk_mul_f32 v[40:41], v[40:41], v[6:7]
	v_pk_mul_f32 v[36:37], v[36:37], v[10:11]
	v_pk_mul_f32 v[46:47], v[46:47], v[4:5]
	v_pk_mul_f32 v[42:43], v[42:43], v[8:9]
	v_pk_mul_f32 v[38:39], v[38:39], v[12:13]
	v_pk_mul_f32 v[34:35], v[34:35], v[114:115]
	v_pk_mul_f32 v[32:33], v[32:33], v[112:113]
	v_pk_mul_f32 v[28:29], v[28:29], v[2:3]
	v_pk_mul_f32 v[24:25], v[24:25], v[6:7]
	v_pk_mul_f32 v[20:21], v[20:21], v[10:11]
	v_pk_mul_f32 v[30:31], v[30:31], v[4:5]
	v_pk_mul_f32 v[26:27], v[26:27], v[8:9]
	v_pk_mul_f32 v[22:23], v[22:23], v[12:13]
	v_pk_mul_f32 v[18:19], v[18:19], v[114:115]
	v_pk_mul_f32 v[16:17], v[16:17], v[112:113]
	v_pk_mul_f32 v[92:93], v[92:93], v[2:3]
	v_pk_mul_f32 v[88:89], v[88:89], v[6:7]
	v_pk_mul_f32 v[84:85], v[84:85], v[10:11]
	v_pk_mul_f32 v[94:95], v[94:95], v[4:5]
	v_pk_mul_f32 v[90:91], v[90:91], v[8:9]
	v_pk_mul_f32 v[86:87], v[86:87], v[12:13]
	v_pk_mul_f32 v[82:83], v[82:83], v[114:115]
	v_pk_mul_f32 v[80:81], v[80:81], v[112:113]
	v_exp_f32_e32 v13, v128
	v_exp_f32_e32 v10, v129
	v_exp_f32_e32 v11, v130
	v_exp_f32_e32 v12, v131

; #define SBAR() __builtin_amdgcn_sched_barrier(0)
; #define QKT(P0, P1, b) qkt(P0, P1, nm, K_lds + (b) * SHM_T, qr, ko, c00, c01, c10, c11)
; #define PIPE1() do { SGB(0x100, 8); SGB(0x400, 4); SGB(0x008, 1); SGB(0x400, 4); SGB(0x008, 1); SGB(0x400, 4); SGB(0x008, 1); SGB(0x400, 4); SGB(0x008, 1); } while (0)
; __device__ __forceinline__ void finishSM(f32x16& p0, f32x16& p1, v8i& pf) {
;   for (int r = 0; r < 16; ++r) p1[r] = __builtin_amdgcn_exp2f(p1[r]);
; #pragma unroll
;   for (int j = 0; j < 4; ++j) {
;     int a = __builtin_amdgcn_cvt_pk_fp8_f32(p0[4 * j], p0[4 * j + 1], 0, false); a = __builtin_amdgcn_cvt_pk_fp8_f32(p0[4 * j + 2], p0[4 * j + 3], a, true);
;     int b = __builtin_amdgcn_cvt_pk_fp8_f32(p1[4 * j], p1[4 * j + 1], 0, false); b = __builtin_amdgcn_cvt_pk_fp8_f32(p1[4 * j + 2], p1[4 * j + 3], b, true);
;     auto rr = __builtin_amdgcn_permlane32_swap((unsigned)a, (unsigned)b, false, false);
;     pf[2 * j] = (int)rr[0]; pf[2 * j + 1] = (int)rr[1]; }
; }
; __device__ __forceinline__ void body(const unsigned char* Q8b, const unsigned char* K8h, const unsigned char* VT8h, const bf16_t* Gb, bf16_t* Ob, int seq, char* lds, const int wid, ...
;     ...
;     SBAR(); QKT(pA0, pA1, (s0 + 2) & 3);
;     finishSM(pB0, pB1, pf); PIPE1(); SBAR();
.Lstg_a1:
	ds_read_b128 v[2:5], v242 offset:49152
	ds_read_b128 v[6:9], v243 offset:49152
	ds_read_b128 v[112:115], v242 offset:53248
	ds_read_b128 v[116:119], v243 offset:53248
	ds_read_b128 v[194:197], v244 offset:49152
	ds_read_b128 v[198:201], v245 offset:49152
	ds_read_b128 v[246:249], v244 offset:53248
	ds_read_b128 v[250:253], v245 offset:53248
	s_waitcnt lgkmcnt(6)
	s_setprio 1
	v_mfma_scale_f32_32x32x64_f8f6f4 v[160:175], v[2:9], v[176:183], v[96:111], v240, v239 op_sel_hi:[0,0,0]
	v_exp_f32_e32 v6, v132
	v_exp_f32_e32 v7, v133
	v_exp_f32_e32 v8, v134
	v_exp_f32_e32 v9, v135
	v_cvt_pk_fp8_f32 v5, v6, v7
	v_cvt_pk_fp8_f32 v2, v144, v145
	v_cvt_pk_fp8_f32 v5, v8, v9 op_sel:[0,0,1]
	s_waitcnt lgkmcnt(4)
	v_mfma_scale_f32_32x32x64_f8f6f4 v[112:127], v[112:119], v[176:183], v[96:111], v240, v239 op_sel_hi:[0,0,0]
	v_cvt_pk_fp8_f32 v3, v13, v10
	v_exp_f32_e32 v13, v136
	v_exp_f32_e32 v14, v137
	v_exp_f32_e32 v15, v138
	v_exp_f32_e32 v128, v139
	v_cvt_pk_fp8_f32 v4, v148, v149
	v_cvt_pk_fp8_f32 v6, v152, v153
	v_cvt_pk_fp8_f32 v7, v13, v14
	v_cvt_pk_fp8_f32 v8, v156, v157
	v_cvt_pk_fp8_f32 v2, v146, v147 op_sel:[0,0,1]
	v_cvt_pk_fp8_f32 v3, v11, v12 op_sel:[0,0,1]
	v_cvt_pk_fp8_f32 v4, v150, v151 op_sel:[0,0,1]
	v_cvt_pk_fp8_f32 v6, v154, v155 op_sel:[0,0,1]
	v_cvt_pk_fp8_f32 v7, v15, v128 op_sel:[0,0,1]
	v_cvt_pk_fp8_f32 v8, v158, v159 op_sel:[0,0,1]
	s_waitcnt lgkmcnt(2)
	v_mfma_scale_f32_32x32x64_f8f6f4 v[160:175], v[194:201], v[184:191], v[160:175], v240, v239 op_sel_hi:[0,0,0]
	v_exp_f32_e32 v129, v140
	v_exp_f32_e32 v130, v141
	v_exp_f32_e32 v131, v142
	v_exp_f32_e32 v132, v143
	v_permlane32_swap_b32_e32 v2, v3
	v_cvt_pk_fp8_f32 v9, v129, v130
	v_permlane32_swap_b32_e32 v4, v5
	v_permlane32_swap_b32_e32 v6, v7
	v_cvt_pk_fp8_f32 v9, v131, v132 op_sel:[0,0,1]
	s_nop 1
	v_permlane32_swap_b32_e32 v8, v9
	s_waitcnt lgkmcnt(0)
	v_mfma_scale_f32_32x32x64_f8f6f4 v[112:127], v[246:253], v[184:191], v[112:127], v240, v239 op_sel_hi:[0,0,0]
	s_setprio 0
	s_min_u32 s36, s45, 0x7b
	s_add_i32 s56, s36, 4
	s_lshl_b32 s36, s56, 14
	s_add_i32 s57, s68, 0x0
	s_add_u32 s88, s94, s36
	s_addc_u32 s89, s95, 0
	s_add_i32 m0, s57, 0x8000
	s_lshl_b32 s36, s56, 13
	s_add_u32 s90, s96, s36
	s_addc_u32 s91, s97, 0
	global_load_lds_dwordx4 v192, s[88:89]
	s_mov_b32 m0, s57
	s_nop 0
	global_load_lds_dwordx4 v193, s[90:91]
	ds_read_b128 v[194:197], v254 offset:8192
	ds_read_b128 v[148:151], v254 offset:10240
	ds_read_b128 v[198:201], v255 offset:8192
	ds_read_b128 v[152:155], v255 offset:10240
	ds_read_b128 v[136:139], v254 offset:12288
	ds_read_b128 v[128:131], v254 offset:14336
	ds_read_b128 v[140:143], v255 offset:12288
	ds_read_b128 v[132:135], v255 offset:14336
	v_max_f32_e32 v1, v160, v161
	v_max3_f32 v1, v1, v162, v163
	v_max3_f32 v1, v1, v164, v165
	v_max3_f32 v1, v1, v166, v167
	v_max3_f32 v1, v1, v168, v169
	v_max3_f32 v1, v1, v170, v171
	v_max3_f32 v1, v1, v172, v173
	v_max3_f32 v1, v1, v174, v175
	v_max3_f32 v1, v1, v112, v113
	v_max3_f32 v1, v1, v114, v115
	v_max3_f32 v1, v1, v116, v117
	v_max3_f32 v1, v1, v118, v119
	v_max3_f32 v1, v1, v120, v121
	v_max3_f32 v1, v1, v122, v123
	v_max3_f32 v1, v1, v124, v125
	v_max3_f32 v1, v1, v126, v127
	v_cmp_lt_f32_e32 vcc, s80, v1
	s_cbranch_vccnz .LBB0_384

; #define BAR() do { asm volatile("s_waitcnt lgkmcnt(0)" ::: "memory"); __builtin_amdgcn_s_barrier(); asm volatile("" ::: "memory"); } while (0)
; #define RESC(a) do { if (__any((a) < 1.f)) { if (hi == 0) al_l[r32] = (a); asm volatile("s_waitcnt lgkmcnt(0)" ::: "memory"); \
;     for (int r = 0; r < 16; ++r) { const float a_ = al_l[crow(r, hi)]; ls[r] *= a_; for (int d = 0; d < 4; ++d) o[d][r] *= a_; } } } while (0)
; __device__ __forceinline__ void body(const unsigned char* Q8b, const unsigned char* K8h, const unsigned char* VT8h, const bf16_t* Gb, bf16_t* Ob, int seq, char* lds, const int wid, ...
;     ...
;     RESC(alB); BAR();
.Lstg_b2:
	s_waitcnt lgkmcnt(5)
	v_mfma_scale_f32_32x32x64_f8f6f4 v[64:79], v[2:9], v[194:201], v[64:79], v240, v240 op_sel_hi:[0,0,0]
	v_exp_f32_e32 v144, v160
	v_exp_f32_e32 v145, v161
	v_exp_f32_e32 v146, v162
	v_exp_f32_e32 v13, v112
	s_waitcnt lgkmcnt(4)
	v_mfma_scale_f32_32x32x64_f8f6f4 v[48:63], v[2:9], v[148:155], v[48:63], v240, v240 op_sel_hi:[0,0,0]
	v_exp_f32_e32 v147, v163
	v_exp_f32_e32 v148, v164
	v_exp_f32_e32 v149, v165
	v_exp_f32_e32 v10, v113
	s_waitcnt lgkmcnt(1)
	v_mfma_scale_f32_32x32x64_f8f6f4 v[32:47], v[2:9], v[136:143], v[32:47], v240, v240 op_sel_hi:[0,0,0]
	v_exp_f32_e32 v150, v166
	v_exp_f32_e32 v151, v167
	v_exp_f32_e32 v152, v168
	v_exp_f32_e32 v11, v114
	s_waitcnt lgkmcnt(0)
	v_mfma_scale_f32_32x32x64_f8f6f4 v[16:31], v[2:9], v[128:135], v[16:31], v240, v240 op_sel_hi:[0,0,0]
	v_exp_f32_e32 v153, v169
	v_exp_f32_e32 v154, v170
	v_exp_f32_e32 v155, v171
	v_exp_f32_e32 v12, v115
	v_mfma_scale_f32_32x32x64_f8f6f4 v[80:95], v[2:9], v[228:235], v[80:95], v240, v240 op_sel_hi:[0,0,0]
	v_exp_f32_e32 v156, v172
	v_exp_f32_e32 v157, v173
	v_exp_f32_e32 v158, v174
	v_exp_f32_e32 v159, v175
	s_waitcnt vmcnt(2)
	s_cmp_eq_u32 s93, 0
	s_cbranch_scc1 .LBB0_373
	s_mov_b32 s93, 0
	s_and_saveexec_b64 s[56:57], s[4:5]
	s_cbranch_execz .LBB0_372
	ds_write_b32 v236, v1 offset:128
	s_branch .LBB0_372

; #define SBAR() __builtin_amdgcn_sched_barrier(0)
; #define QKT(P0, P1, b) qkt(P0, P1, nm, K_lds + (b) * SHM_T, qr, ko, c00, c01, c10, c11)
; #define PIPE1() do { SGB(0x100, 8); SGB(0x400, 4); SGB(0x008, 1); SGB(0x400, 4); SGB(0x008, 1); SGB(0x400, 4); SGB(0x008, 1); SGB(0x400, 4); SGB(0x008, 1); } while (0)
; __device__ __forceinline__ void finishSM(f32x16& p0, f32x16& p1, v8i& pf) {
;   for (int r = 0; r < 16; ++r) p1[r] = __builtin_amdgcn_exp2f(p1[r]);
; #pragma unroll
;   for (int j = 0; j < 4; ++j) {
;     int a = __builtin_amdgcn_cvt_pk_fp8_f32(p0[4 * j], p0[4 * j + 1], 0, false); a = __builtin_amdgcn_cvt_pk_fp8_f32(p0[4 * j + 2], p0[4 * j + 3], a, true);
;     int b = __builtin_amdgcn_cvt_pk_fp8_f32(p1[4 * j], p1[4 * j + 1], 0, false); b = __builtin_amdgcn_cvt_pk_fp8_f32(p1[4 * j + 2], p1[4 * j + 3], b, true);
;     auto rr = __builtin_amdgcn_permlane32_swap((unsigned)a, (unsigned)b, false, false);
;     pf[2 * j] = (int)rr[0]; pf[2 * j + 1] = (int)rr[1]; }
; }
; __device__ __forceinline__ void body(const unsigned char* Q8b, const unsigned char* K8h, const unsigned char* VT8h, const bf16_t* Gb, bf16_t* Ob, int seq, char* lds, const int wid, ...
;     ...
;     SBAR(); QKT(pB0, pB1, (s0 + 1) & 3);
;     finishSM(pA0, pA1, pf); PIPE1(); SBAR();
.Lc2_374:
	ds_read_b128 v[2:5], v242 offset:57344
	ds_read_b128 v[6:9], v243 offset:57344
	ds_read_b128 v[128:131], v242 offset:61440
	ds_read_b128 v[132:135], v243 offset:61440
	ds_read_b128 v[194:197], v244 offset:57344
	ds_read_b128 v[198:201], v245 offset:57344
	ds_read_b128 v[246:249], v244 offset:61440
	ds_read_b128 v[250:253], v245 offset:61440
	s_waitcnt lgkmcnt(6)
	s_setprio 1
	v_mfma_scale_f32_32x32x64_f8f6f4 v[160:175], v[2:9], v[176:183], v[96:111], v240, v239 op_sel_hi:[0,0,0]
	v_exp_f32_e32 v6, v116
	v_exp_f32_e32 v7, v117
	v_exp_f32_e32 v8, v118
	v_exp_f32_e32 v9, v119
	v_cvt_pk_fp8_f32 v5, v6, v7
	v_cvt_pk_fp8_f32 v3, v13, v10
	v_cvt_pk_fp8_f32 v5, v8, v9 op_sel:[0,0,1]
	s_waitcnt lgkmcnt(4)
	v_mfma_scale_f32_32x32x64_f8f6f4 v[128:143], v[128:135], v[176:183], v[96:111], v240, v239 op_sel_hi:[0,0,0]
	v_exp_f32_e32 v13, v120
	v_exp_f32_e32 v14, v121
	v_exp_f32_e32 v15, v122
	v_exp_f32_e32 v112, v123
	v_cvt_pk_fp8_f32 v2, v144, v145
	v_cvt_pk_fp8_f32 v4, v148, v149
	v_cvt_pk_fp8_f32 v6, v152, v153
	v_cvt_pk_fp8_f32 v7, v13, v14
	v_cvt_pk_fp8_f32 v8, v156, v157
	v_cvt_pk_fp8_f32 v2, v146, v147 op_sel:[0,0,1]
	v_cvt_pk_fp8_f32 v3, v11, v12 op_sel:[0,0,1]
	v_cvt_pk_fp8_f32 v4, v150, v151 op_sel:[0,0,1]
	v_cvt_pk_fp8_f32 v6, v154, v155 op_sel:[0,0,1]
	v_cvt_pk_fp8_f32 v7, v15, v112 op_sel:[0,0,1]
	v_cvt_pk_fp8_f32 v8, v158, v159 op_sel:[0,0,1]
	s_waitcnt lgkmcnt(2)
	v_mfma_scale_f32_32x32x64_f8f6f4 v[160:175], v[194:201], v[184:191], v[160:175], v240, v239 op_sel_hi:[0,0,0]
	v_exp_f32_e32 v113, v124
	v_exp_f32_e32 v114, v125
	v_exp_f32_e32 v1, v126
	v_exp_f32_e32 v10, v127
	v_permlane32_swap_b32_e32 v2, v3
	v_cvt_pk_fp8_f32 v9, v113, v114
	v_permlane32_swap_b32_e32 v4, v5
	v_permlane32_swap_b32_e32 v6, v7
	v_cvt_pk_fp8_f32 v9, v1, v10 op_sel:[0,0,1]
	s_nop 1
	v_permlane32_swap_b32_e32 v8, v9
	s_waitcnt lgkmcnt(0)
	v_mfma_scale_f32_32x32x64_f8f6f4 v[128:143], v[246:253], v[184:191], v[128:143], v240, v239 op_sel_hi:[0,0,0]
	s_setprio 0
	s_add_i32 m0, s68, 0xa000
	s_nop 0
	global_load_lds_dwordx4 v192, s[98:99]
	s_add_i32 m0, s68, 0x2000
	s_nop 0
	global_load_lds_dwordx4 v193, s[100:101]
	ds_read_b128 v[194:197], v254 offset:16384
	ds_read_b128 v[148:151], v254 offset:18432
	ds_read_b128 v[198:201], v255 offset:16384
	ds_read_b128 v[152:155], v255 offset:18432
	ds_read_b128 v[120:123], v254 offset:20480
	ds_read_b128 v[112:115], v254 offset:22528
	ds_read_b128 v[124:127], v255 offset:20480
	ds_read_b128 v[116:119], v255 offset:22528
	v_max_f32_e32 v1, v160, v161
	v_max3_f32 v1, v1, v162, v163
	v_max3_f32 v1, v1, v164, v165
	v_max3_f32 v1, v1, v166, v167
	v_max3_f32 v1, v1, v168, v169
	v_max3_f32 v1, v1, v170, v171
	v_max3_f32 v1, v1, v172, v173
	v_max3_f32 v1, v1, v174, v175
	v_max3_f32 v1, v1, v128, v129
	v_max3_f32 v1, v1, v130, v131
	v_max3_f32 v1, v1, v132, v133
	v_max3_f32 v1, v1, v134, v135
	v_max3_f32 v1, v1, v136, v137
	v_max3_f32 v1, v1, v138, v139
	v_max3_f32 v1, v1, v140, v141
	v_max3_f32 v1, v1, v142, v143
	v_cmp_lt_f32_e32 vcc, s80, v1
	s_cbranch_vccnz .Lc2_383

; #define SBAR() __builtin_amdgcn_sched_barrier(0)
; #define MFMA8Q(A, B, C) __builtin_amdgcn_mfma_scale_f32_32x32x64_f8f6f4(A, B, C, 0, 0, 0, SCL1, 0, 0x7C7C7C7C)
; __device__ __forceinline__ v8i ld32(const char* p0, const char* p1) { const u32x4 a = *(const u32x4*)p0, b = *(const u32x4*)p1; return (v8i){(int)a.x, (int)a.y, (int)a.z, (int)a.w, (int)b.x, (int)b.y, (int)b.z, (int)b.w}; }
; #define DMA(slot, t) do { \
;     __builtin_amdgcn_global_load_lds((const unsigned*)(Kg + (long)(t) * (64 * 256)), (LAS unsigned*)(L3 + K_OFF + (slot) * SHM_T + wid * 1024), 16, 0, 0); \
;     __builtin_amdgcn_global_load_lds((const unsigned*)(Vg + (long)(t) * 8192), (LAS unsigned*)(L3 + (slot) * SHM_T + wid * 1024), 16, 0, 0); } while (0)
; __device__ __forceinline__ void finishSM(f32x16& p0, f32x16& p1, v8i& pf) {
;   for (int r = 0; r < 16; ++r) p1[r] = __builtin_amdgcn_exp2f(p1[r]);
; #pragma unroll
;   for (int j = 0; j < 4; ++j) {
;     int a = __builtin_amdgcn_cvt_pk_fp8_f32(p0[4 * j], p0[4 * j + 1], 0, false); a = __builtin_amdgcn_cvt_pk_fp8_f32(p0[4 * j + 2], p0[4 * j + 3], a, true);
;     int b = __builtin_amdgcn_cvt_pk_fp8_f32(p1[4 * j], p1[4 * j + 1], 0, false); b = __builtin_amdgcn_cvt_pk_fp8_f32(p1[4 * j + 2], p1[4 * j + 3], b, true);
;     auto rr = __builtin_amdgcn_permlane32_swap((unsigned)a, (unsigned)b, false, false);
;     pf[2 * j] = (int)rr[0]; pf[2 * j + 1] = (int)rr[1]; }
; }
; __device__ __forceinline__ void qkt(f32x16& p0, f32x16& p1, const f32x16& nm, const char* Ks, const v8i* qr, int ko, int c00, int c01, int c10, int c11) {
;   { const v8i a0 = ld32(Ks + ko + c00, Ks + ko + c01), a1 = ld32(Ks + 4096 + ko + c00, Ks + 4096 + ko + c01);
;     p0 = MFMA8Q(a0, qr[0], nm); p1 = MFMA8Q(a1, qr[0], nm); }
;   { const v8i a0 = ld32(Ks + ko + c10, Ks + ko + c11), a1 = ld32(Ks + 4096 + ko + c10, Ks + 4096 + ko + c11);
;     p0 = MFMA8Q(a0, qr[1], p0); p1 = MFMA8Q(a1, qr[1], p1); }
; }
; __device__ __forceinline__ void body(const unsigned char* Q8b, const unsigned char* K8h, const unsigned char* VT8h, const bf16_t* Gb, bf16_t* Ob, int seq, char* lds, const int wid, ...
;     ...
;     SBAR(); QKT(pA0, pA1, (s0 + 2) & 3);
;     finishSM(pB0, pB1, pf); PIPE1(); SBAR();
;     { const int t4 = (i + 4 < NT) ? i + 4 : NT - 1; DMA(s0, t4); }
;     SBAR();
;     HALF2(pA0, pA1, alA, (s0 + 1) & 3);
.Lc2stg_a1:
	ds_read_b128 v[2:5], v242 offset:32768
	ds_read_b128 v[6:9], v243 offset:32768
	ds_read_b128 v[112:115], v242 offset:36864
	ds_read_b128 v[116:119], v243 offset:36864
	ds_read_b128 v[194:197], v244 offset:32768
	ds_read_b128 v[198:201], v245 offset:32768
	ds_read_b128 v[246:249], v244 offset:36864
	ds_read_b128 v[250:253], v245 offset:36864
	s_waitcnt lgkmcnt(6)
	s_setprio 1
	v_mfma_scale_f32_32x32x64_f8f6f4 v[160:175], v[2:9], v[176:183], v[96:111], v240, v239 op_sel_hi:[0,0,0]
	v_exp_f32_e32 v6, v132
	v_exp_f32_e32 v7, v133
	v_exp_f32_e32 v8, v134
	v_exp_f32_e32 v9, v135
	v_cvt_pk_fp8_f32 v5, v6, v7
	v_cvt_pk_fp8_f32 v2, v144, v145
	v_cvt_pk_fp8_f32 v5, v8, v9 op_sel:[0,0,1]
	s_waitcnt lgkmcnt(4)
	v_mfma_scale_f32_32x32x64_f8f6f4 v[112:127], v[112:119], v[176:183], v[96:111], v240, v239 op_sel_hi:[0,0,0]
	v_cvt_pk_fp8_f32 v3, v13, v10
	v_exp_f32_e32 v13, v136
	v_exp_f32_e32 v14, v137
	v_exp_f32_e32 v15, v138
	v_exp_f32_e32 v128, v139
	v_cvt_pk_fp8_f32 v4, v148, v149
	v_cvt_pk_fp8_f32 v6, v152, v153
	v_cvt_pk_fp8_f32 v7, v13, v14
	v_cvt_pk_fp8_f32 v8, v156, v157
	v_cvt_pk_fp8_f32 v2, v146, v147 op_sel:[0,0,1]
	v_cvt_pk_fp8_f32 v3, v11, v12 op_sel:[0,0,1]
	v_cvt_pk_fp8_f32 v4, v150, v151 op_sel:[0,0,1]
	v_cvt_pk_fp8_f32 v6, v154, v155 op_sel:[0,0,1]
	v_cvt_pk_fp8_f32 v7, v15, v128 op_sel:[0,0,1]
	v_cvt_pk_fp8_f32 v8, v158, v159 op_sel:[0,0,1]
	s_waitcnt lgkmcnt(2)
	v_mfma_scale_f32_32x32x64_f8f6f4 v[160:175], v[194:201], v[184:191], v[160:175], v240, v239 op_sel_hi:[0,0,0]
	v_exp_f32_e32 v129, v140
	v_exp_f32_e32 v130, v141
	v_exp_f32_e32 v131, v142
	v_exp_f32_e32 v132, v143
	v_permlane32_swap_b32_e32 v2, v3
	v_cvt_pk_fp8_f32 v9, v129, v130
	v_permlane32_swap_b32_e32 v4, v5
	v_permlane32_swap_b32_e32 v6, v7
	v_cvt_pk_fp8_f32 v9, v131, v132 op_sel:[0,0,1]
	s_nop 1
	v_permlane32_swap_b32_e32 v8, v9
	s_waitcnt lgkmcnt(0)
	v_mfma_scale_f32_32x32x64_f8f6f4 v[112:127], v[246:253], v[184:191], v[112:127], v240, v239 op_sel_hi:[0,0,0]
	s_setprio 0
	s_min_u32 s36, s45, 0x7b
	s_add_i32 s56, s36, 4
	s_lshl_b32 s36, s56, 14
	s_add_i32 s57, s68, 0x4000
	s_add_u32 s88, s94, s36
	s_addc_u32 s89, s95, 0
	s_add_i32 m0, s57, 0x8000
	s_lshl_b32 s36, s56, 13
	s_add_u32 s90, s96, s36
	s_addc_u32 s91, s97, 0
	global_load_lds_dwordx4 v192, s[88:89]
	s_mov_b32 m0, s57
	s_nop 0
	global_load_lds_dwordx4 v193, s[90:91]
	ds_read_b128 v[194:197], v254 offset:24576
	ds_read_b128 v[148:151], v254 offset:26624
	ds_read_b128 v[198:201], v255 offset:24576
	ds_read_b128 v[152:155], v255 offset:26624
	ds_read_b128 v[136:139], v254 offset:28672
	ds_read_b128 v[128:131], v254 offset:30720
	ds_read_b128 v[140:143], v255 offset:28672
	ds_read_b128 v[132:135], v255 offset:30720
	v_max_f32_e32 v1, v160, v161
	v_max3_f32 v1, v1, v162, v163
	v_max3_f32 v1, v1, v164, v165
	v_max3_f32 v1, v1, v166, v167
	v_max3_f32 v1, v1, v168, v169
	v_max3_f32 v1, v1, v170, v171
	v_max3_f32 v1, v1, v172, v173
	v_max3_f32 v1, v1, v174, v175
	v_max3_f32 v1, v1, v112, v113
	v_max3_f32 v1, v1, v114, v115
	v_max3_f32 v1, v1, v116, v117
	v_max3_f32 v1, v1, v118, v119
	v_max3_f32 v1, v1, v120, v121
	v_max3_f32 v1, v1, v122, v123
	v_max3_f32 v1, v1, v124, v125
	v_max3_f32 v1, v1, v126, v127
	v_cmp_lt_f32_e32 vcc, s80, v1
	s_cbranch_vccnz .Lc2_384
